# baseline (speedup 1.0000x reference)
; #define PG8_STAGE(bufoff, gbase, voff) do { _Pragma("unroll") for (int _i = 0; _i < 2; ++_i) \
;         __builtin_amdgcn_global_load_lds((const unsigned*)((const char*)(gbase) + (voff)[_i]), (PG8_LAS unsigned*)(lds + (bufoff) + ldsw + _i * 8192), 16, 0, 0); } while (0)
; #define PG8_LDA(dst, b, h) do { _Pragma("unroll") for (int m = 0; m < 4; ++m) _Pragma("unroll") for (int k = 0; k < 2; ++k) dst[m][k] = *(const PG8_LAS bf16x8*)(lds + PG8_SA(b, h) + aoff + m * 2048 + k * 1024); } while (0)
; #define PG8_LDB(dst, b, h) do { _Pragma("unroll") for (int n = 0; n < 2; ++n) _Pragma("unroll") for (int k = 0; k < 2; ++k) dst[n][k] = *(const PG8_LAS bf16x8*)(lds + PG8_SB(b, h) + boff + n * 2048 + k * 1024); } while (0)
; #define PG8_MMA(ai, bj, At, Bt) do { __builtin_amdgcn_s_setprio(1); _Pragma("unroll") for (int m = 0; m < 4; ++m) _Pragma("unroll") for (int n = 0; n < 2; ++n) _Pragma("unroll") for (int k = 0; k < 2; ++k) \
;         acc[ai][bj][m][n] = __builtin_amdgcn_mfma_f32_16x16x32_bf16(Bt[n][k], At[m][k], acc[ai][bj][m][n], 0, 0, 0); __builtin_amdgcn_s_setprio(0); } while (0)
; #define PG8_WAIT_V(n) asm volatile("s_waitcnt vmcnt(" #n ")" ::: "memory")
; #define PG8_WAIT_L(n) asm volatile("s_waitcnt lgkmcnt(" #n ")" ::: "memory")
; #define PG8_BAR __builtin_amdgcn_s_barrier()
; #define PG8_SCHED __builtin_amdgcn_sched_barrier(0)
; template <class Epi, class Sched, bool ALIGN_EPI = false, bool SP2 = false, bool AIMG = false>
; __device__ __forceinline__ void gemm_phase(PG8_LAS unsigned char* lds, const Gemm g, const Sched& S, const Epi& E) {
;     ...
;             PG8_LDB(B0, 0, 0); PG8_LDB(B1, 0, 1); PG8_SCHED; PG8_LDA(At, 0, 0); PG8_STAGE(PG8_SA(1, 1), a1 + hstep, voffA);
;             PG8_WAIT_V(8); PG8_WAIT_L(0); PG8_BAR; PG8_MMA(0, 0, At, B0); PG8_MMA(0, 1, At, B1); PG8_BAR; PG8_SCHED;
;             PG8_LDA(At, 0, 1); PG8_STAGE(PG8_SB(0, 0), b2, voffB); PG8_STAGE(PG8_SB(0, 1), b2 + hstep, voffB); PG8_STAGE(PG8_SA(0, 0), a2, voffA);
;             PG8_WAIT_V(8); PG8_WAIT_L(0); PG8_BAR; PG8_MMA(1, 0, At, B0); PG8_MMA(1, 1, At, B1); PG8_BAR; PG8_SCHED;
.LBB0_286:
	s_add_u32 s36, s28, 0xfffc0080
	s_addc_u32 s37, s29, -1
	s_add_i32 s57, 0, 0x10000
	s_cmp_eq_u32 s56, 12
	s_cselect_b32 s41, s21, s37
	s_cselect_b32 s40, s35, s36
	s_cselect_b32 s37, s11, s55
	s_cselect_b32 s36, s38, s54
	s_add_i32 s60, 0, 0x14000
	v_add_u32_e32 v140, s57, v186
	v_add_u32_e32 v144, s60, v186
	ds_read_b128 v[128:131], v140
	ds_read_b128 v[132:135], v140 offset:1024
	ds_read_b128 v[136:139], v140 offset:2048
	ds_read_b128 v[140:143], v140 offset:3072
	s_waitcnt lgkmcnt(4)
	ds_read_b128 v[170:173], v144
	ds_read_b128 v[174:177], v144 offset:1024
	ds_read_b128 v[178:181], v144 offset:2048
	ds_read_b128 v[182:185], v144 offset:3072
	v_lshl_add_u64 v[198:199], s[28:29], 0, v[166:167]
	s_add_i32 m0, s42, 0xc000
	ds_read_b128 v[190:193], v188
	ds_read_b128 v[216:219], v188 offset:1024
	ds_read_b128 v[220:223], v188 offset:2048
	ds_read_b128 v[224:227], v188 offset:3072
	ds_read_b128 v[228:231], v188 offset:4096
	ds_read_b128 v[232:235], v188 offset:5120
	ds_read_b128 v[236:239], v188 offset:6144
	ds_read_b128 v[240:243], v188 offset:7168
	global_load_lds_dwordx4 v[198:199], off
	v_lshl_add_u64 v[198:199], s[28:29], 0, v[168:169]
	s_add_i32 m0, s42, 0xe000
	s_nop 0
	global_load_lds_dwordx4 v[198:199], off
	s_waitcnt vmcnt(8)
	s_waitcnt lgkmcnt(0)
	s_barrier
	s_setprio 1
	s_waitcnt lgkmcnt(0)
	v_mfma_f32_16x16x32_bf16 v[124:127], v[128:131], v[190:193], v[124:127]
	v_mfma_f32_16x16x32_bf16 v[116:119], v[136:139], v[190:193], v[116:119]
	v_mfma_f32_16x16x32_bf16 v[108:111], v[128:131], v[220:223], v[108:111]
	v_mfma_f32_16x16x32_bf16 v[100:103], v[136:139], v[220:223], v[100:103]
	v_mfma_f32_16x16x32_bf16 v[92:95], v[128:131], v[228:231], v[92:95]
	v_mfma_f32_16x16x32_bf16 v[84:87], v[136:139], v[228:231], v[84:87]
	v_mfma_f32_16x16x32_bf16 v[76:79], v[128:131], v[236:239], v[76:79]
	v_mfma_f32_16x16x32_bf16 v[68:71], v[136:139], v[236:239], v[68:71]
	v_mfma_f32_16x16x32_bf16 v[124:127], v[132:135], v[216:219], v[124:127]
	v_mfma_f32_16x16x32_bf16 v[116:119], v[140:143], v[216:219], v[116:119]
	v_mfma_f32_16x16x32_bf16 v[108:111], v[132:135], v[224:227], v[108:111]
	v_mfma_f32_16x16x32_bf16 v[100:103], v[140:143], v[224:227], v[100:103]
	v_mfma_f32_16x16x32_bf16 v[92:95], v[132:135], v[232:235], v[92:95]
	v_mfma_f32_16x16x32_bf16 v[84:87], v[140:143], v[232:235], v[84:87]
	v_mfma_f32_16x16x32_bf16 v[76:79], v[132:135], v[240:243], v[76:79]
	v_mfma_f32_16x16x32_bf16 v[68:71], v[140:143], v[240:243], v[68:71]
	s_setprio 0
	s_setprio 1
	v_mfma_f32_16x16x32_bf16 v[120:123], v[170:173], v[190:193], v[120:123]
	v_mfma_f32_16x16x32_bf16 v[112:115], v[178:181], v[190:193], v[112:115]
	v_mfma_f32_16x16x32_bf16 v[104:107], v[170:173], v[220:223], v[104:107]
	v_mfma_f32_16x16x32_bf16 v[96:99], v[178:181], v[220:223], v[96:99]
	v_mfma_f32_16x16x32_bf16 v[88:91], v[170:173], v[228:231], v[88:91]
	v_mfma_f32_16x16x32_bf16 v[80:83], v[178:181], v[228:231], v[80:83]
	v_mfma_f32_16x16x32_bf16 v[72:75], v[170:173], v[236:239], v[72:75]
	v_mfma_f32_16x16x32_bf16 v[64:67], v[178:181], v[236:239], v[64:67]
	v_mfma_f32_16x16x32_bf16 v[120:123], v[174:177], v[216:219], v[120:123]
	v_mfma_f32_16x16x32_bf16 v[112:115], v[182:185], v[216:219], v[112:115]
	v_mfma_f32_16x16x32_bf16 v[104:107], v[174:177], v[224:227], v[104:107]
	v_mfma_f32_16x16x32_bf16 v[96:99], v[182:185], v[224:227], v[96:99]
	v_mfma_f32_16x16x32_bf16 v[88:91], v[174:177], v[232:235], v[88:91]
	v_mfma_f32_16x16x32_bf16 v[80:83], v[182:185], v[232:235], v[80:83]
	v_mfma_f32_16x16x32_bf16 v[72:75], v[174:177], v[240:243], v[72:75]
	v_mfma_f32_16x16x32_bf16 v[64:67], v[182:185], v[240:243], v[64:67]
	s_setprio 0
	s_barrier
	s_add_i32 s57, s57, s4
	v_lshl_add_u64 v[198:199], s[36:37], 0, v[156:157]
	s_mov_b32 m0, s57
	ds_read_b128 v[190:193], v188 offset:16384
	ds_read_b128 v[216:219], v188 offset:17408
	ds_read_b128 v[220:223], v188 offset:18432
	ds_read_b128 v[224:227], v188 offset:19456
	ds_read_b128 v[228:231], v188 offset:20480
	ds_read_b128 v[232:235], v188 offset:21504
	ds_read_b128 v[236:239], v188 offset:22528
	ds_read_b128 v[240:243], v188 offset:23552
	global_load_lds_dwordx4 v[198:199], off
	s_add_i32 m0, s57, 0x2000
	s_add_u32 s58, s36, 0x40000
	v_lshl_add_u64 v[200:201], s[36:37], 0, v[152:153]
	s_addc_u32 s59, s37, 0
	s_add_i32 s57, s60, s4
	global_load_lds_dwordx4 v[200:201], off
	v_lshl_add_u64 v[204:205], s[58:59], 0, v[156:157]
	s_mov_b32 m0, s57
	v_lshl_add_u64 v[206:207], s[40:41], 0, v[154:155]
	global_load_lds_dwordx4 v[204:205], off
	v_lshl_add_u64 v[204:205], s[58:59], 0, v[152:153]
	s_add_i32 m0, s57, 0x2000
	s_nop 0
	global_load_lds_dwordx4 v[204:205], off
	v_lshl_add_u64 v[204:205], s[40:41], 0, v[158:159]
	s_mov_b32 m0, s42
	s_nop 0
	global_load_lds_dwordx4 v[204:205], off
	s_mov_b32 m0, s43
	s_nop 0
	global_load_lds_dwordx4 v[206:207], off
	s_waitcnt vmcnt(8)
	s_waitcnt lgkmcnt(0)
	s_barrier
; #define PG8_STAGE(bufoff, gbase, voff) do { _Pragma("unroll") for (int _i = 0; _i < 2; ++_i) \
;         __builtin_amdgcn_global_load_lds((const unsigned*)((const char*)(gbase) + (voff)[_i]), (PG8_LAS unsigned*)(lds + (bufoff) + ldsw + _i * 8192), 16, 0, 0); } while (0)
; #define PG8_LDA(dst, b, h) do { _Pragma("unroll") for (int m = 0; m < 4; ++m) _Pragma("unroll") for (int k = 0; k < 2; ++k) dst[m][k] = *(const PG8_LAS bf16x8*)(lds + PG8_SA(b, h) + aoff + m * 2048 + k * 1024); } while (0)
; #define PG8_LDB(dst, b, h) do { _Pragma("unroll") for (int n = 0; n < 2; ++n) _Pragma("unroll") for (int k = 0; k < 2; ++k) dst[n][k] = *(const PG8_LAS bf16x8*)(lds + PG8_SB(b, h) + boff + n * 2048 + k * 1024); } while (0)
; #define PG8_MMA(ai, bj, At, Bt) do { __builtin_amdgcn_s_setprio(1); _Pragma("unroll") for (int m = 0; m < 4; ++m) _Pragma("unroll") for (int n = 0; n < 2; ++n) _Pragma("unroll") for (int k = 0; k < 2; ++k) \
;         acc[ai][bj][m][n] = __builtin_amdgcn_mfma_f32_16x16x32_bf16(Bt[n][k], At[m][k], acc[ai][bj][m][n], 0, 0, 0); __builtin_amdgcn_s_setprio(0); } while (0)
; #define PG8_WAIT_V(n) asm volatile("s_waitcnt vmcnt(" #n ")" ::: "memory")
; #define PG8_WAIT_L(n) asm volatile("s_waitcnt lgkmcnt(" #n ")" ::: "memory")
; #define PG8_BAR __builtin_amdgcn_s_barrier()
; #define PG8_SCHED __builtin_amdgcn_sched_barrier(0)
; template <class Epi, class Sched, bool ALIGN_EPI = false, bool SP2 = false, bool AIMG = false>
; __device__ __forceinline__ void gemm_phase(PG8_LAS unsigned char* lds, const Gemm g, const Sched& S, const Epi& E) {
;     ...
;             PG8_WAIT_V(8); PG8_WAIT_L(0); PG8_BAR; PG8_MMA(1, 0, At, B0); PG8_MMA(1, 1, At, B1); PG8_BAR; PG8_SCHED;
;             PG8_LDB(B0, 1, 0); PG8_LDB(B1, 1, 1); PG8_SCHED; PG8_LDA(At, 1, 0); PG8_STAGE(PG8_SA(0, 1), a2 + hstep, voffA);
;             PG8_WAIT_V(8); PG8_WAIT_L(0); PG8_BAR; PG8_MMA(0, 0, At, B0); PG8_MMA(0, 1, At, B1); PG8_BAR; PG8_SCHED;
	s_setprio 1
	s_waitcnt lgkmcnt(0)
	v_mfma_f32_16x16x32_bf16 v[60:63], v[128:131], v[190:193], v[60:63]
	v_mfma_f32_16x16x32_bf16 v[52:55], v[136:139], v[190:193], v[52:55]
	v_mfma_f32_16x16x32_bf16 v[44:47], v[128:131], v[220:223], v[44:47]
	v_mfma_f32_16x16x32_bf16 v[36:39], v[136:139], v[220:223], v[36:39]
	v_mfma_f32_16x16x32_bf16 v[28:31], v[128:131], v[228:231], v[28:31]
	v_mfma_f32_16x16x32_bf16 v[20:23], v[136:139], v[228:231], v[20:23]
	v_mfma_f32_16x16x32_bf16 v[12:15], v[128:131], v[236:239], v[12:15]
	v_mfma_f32_16x16x32_bf16 v[4:7], v[136:139], v[236:239], v[4:7]
	v_mfma_f32_16x16x32_bf16 v[60:63], v[132:135], v[216:219], v[60:63]
	v_mfma_f32_16x16x32_bf16 v[52:55], v[140:143], v[216:219], v[52:55]
	v_mfma_f32_16x16x32_bf16 v[44:47], v[132:135], v[224:227], v[44:47]
	v_mfma_f32_16x16x32_bf16 v[36:39], v[140:143], v[224:227], v[36:39]
	v_mfma_f32_16x16x32_bf16 v[28:31], v[132:135], v[232:235], v[28:31]
	v_mfma_f32_16x16x32_bf16 v[20:23], v[140:143], v[232:235], v[20:23]
	v_mfma_f32_16x16x32_bf16 v[12:15], v[132:135], v[240:243], v[12:15]
	v_mfma_f32_16x16x32_bf16 v[4:7], v[140:143], v[240:243], v[4:7]
	s_setprio 0
	s_setprio 1
	v_mfma_f32_16x16x32_bf16 v[56:59], v[170:173], v[190:193], v[56:59]
	v_mfma_f32_16x16x32_bf16 v[48:51], v[178:181], v[190:193], v[48:51]
	v_mfma_f32_16x16x32_bf16 v[40:43], v[170:173], v[220:223], v[40:43]
	v_mfma_f32_16x16x32_bf16 v[32:35], v[178:181], v[220:223], v[32:35]
	v_mfma_f32_16x16x32_bf16 v[24:27], v[170:173], v[228:231], v[24:27]
	v_mfma_f32_16x16x32_bf16 v[16:19], v[178:181], v[228:231], v[16:19]
	v_mfma_f32_16x16x32_bf16 v[8:11], v[170:173], v[236:239], v[8:11]
	v_mfma_f32_16x16x32_bf16 v[0:3], v[178:181], v[236:239], v[0:3]
	v_mfma_f32_16x16x32_bf16 v[56:59], v[174:177], v[216:219], v[56:59]
	v_mfma_f32_16x16x32_bf16 v[48:51], v[182:185], v[216:219], v[48:51]
	v_mfma_f32_16x16x32_bf16 v[40:43], v[174:177], v[224:227], v[40:43]
	v_mfma_f32_16x16x32_bf16 v[32:35], v[182:185], v[224:227], v[32:35]
	v_mfma_f32_16x16x32_bf16 v[24:27], v[174:177], v[232:235], v[24:27]
	v_mfma_f32_16x16x32_bf16 v[16:19], v[182:185], v[232:235], v[16:19]
	v_mfma_f32_16x16x32_bf16 v[8:11], v[174:177], v[240:243], v[8:11]
	v_mfma_f32_16x16x32_bf16 v[0:3], v[182:185], v[240:243], v[0:3]
	s_setprio 0
	s_barrier
	s_add_i32 s57, 0, 0x18000
	s_add_i32 s58, 0, 0x1c000
	v_add_u32_e32 v140, s57, v186
	v_add_u32_e32 v144, s58, v186
	ds_read_b128 v[128:131], v140
	ds_read_b128 v[132:135], v140 offset:1024
	ds_read_b128 v[136:139], v140 offset:2048
	ds_read_b128 v[140:143], v140 offset:3072
	ds_read_b128 v[170:173], v144
	ds_read_b128 v[174:177], v144 offset:1024
	ds_read_b128 v[178:181], v144 offset:2048
	ds_read_b128 v[182:185], v144 offset:3072
	s_add_u32 s40, s40, 0x40000
	s_addc_u32 s41, s41, 0
	s_mov_b32 m0, s44
	v_lshl_add_u64 v[244:245], s[40:41], 0, v[158:159]
	ds_read_b128 v[190:193], v188 offset:32768
	ds_read_b128 v[216:219], v188 offset:33792
	ds_read_b128 v[220:223], v188 offset:34816
	ds_read_b128 v[224:227], v188 offset:35840
	ds_read_b128 v[228:231], v188 offset:36864
	ds_read_b128 v[232:235], v188 offset:37888
	ds_read_b128 v[236:239], v188 offset:38912
	ds_read_b128 v[240:243], v188 offset:39936
	global_load_lds_dwordx4 v[244:245], off
	v_lshl_add_u64 v[244:245], s[40:41], 0, v[154:155]
	s_mov_b32 m0, s45
	s_nop 0
	global_load_lds_dwordx4 v[244:245], off
	s_waitcnt vmcnt(8)
	s_waitcnt lgkmcnt(0)
	s_barrier
	s_setprio 1
	s_waitcnt lgkmcnt(0)
	v_mfma_f32_16x16x32_bf16 v[124:127], v[128:131], v[190:193], v[124:127]
	v_mfma_f32_16x16x32_bf16 v[116:119], v[136:139], v[190:193], v[116:119]
	v_mfma_f32_16x16x32_bf16 v[108:111], v[128:131], v[220:223], v[108:111]
	v_mfma_f32_16x16x32_bf16 v[100:103], v[136:139], v[220:223], v[100:103]
	v_mfma_f32_16x16x32_bf16 v[92:95], v[128:131], v[228:231], v[92:95]
	v_mfma_f32_16x16x32_bf16 v[84:87], v[136:139], v[228:231], v[84:87]
	v_mfma_f32_16x16x32_bf16 v[76:79], v[128:131], v[236:239], v[76:79]
	v_mfma_f32_16x16x32_bf16 v[68:71], v[136:139], v[236:239], v[68:71]
	v_mfma_f32_16x16x32_bf16 v[124:127], v[132:135], v[216:219], v[124:127]
	v_mfma_f32_16x16x32_bf16 v[116:119], v[140:143], v[216:219], v[116:119]
	v_mfma_f32_16x16x32_bf16 v[108:111], v[132:135], v[224:227], v[108:111]
	v_mfma_f32_16x16x32_bf16 v[100:103], v[140:143], v[224:227], v[100:103]
	v_mfma_f32_16x16x32_bf16 v[92:95], v[132:135], v[232:235], v[92:95]
	v_mfma_f32_16x16x32_bf16 v[84:87], v[140:143], v[232:235], v[84:87]
	v_mfma_f32_16x16x32_bf16 v[76:79], v[132:135], v[240:243], v[76:79]
	v_mfma_f32_16x16x32_bf16 v[68:71], v[140:143], v[240:243], v[68:71]
	s_setprio 0
	s_setprio 1
	v_mfma_f32_16x16x32_bf16 v[120:123], v[170:173], v[190:193], v[120:123]
	v_mfma_f32_16x16x32_bf16 v[112:115], v[178:181], v[190:193], v[112:115]
	v_mfma_f32_16x16x32_bf16 v[104:107], v[170:173], v[220:223], v[104:107]
	v_mfma_f32_16x16x32_bf16 v[96:99], v[178:181], v[220:223], v[96:99]
	v_mfma_f32_16x16x32_bf16 v[88:91], v[170:173], v[228:231], v[88:91]
	v_mfma_f32_16x16x32_bf16 v[80:83], v[178:181], v[228:231], v[80:83]
	v_mfma_f32_16x16x32_bf16 v[72:75], v[170:173], v[236:239], v[72:75]
	v_mfma_f32_16x16x32_bf16 v[64:67], v[178:181], v[236:239], v[64:67]
	v_mfma_f32_16x16x32_bf16 v[120:123], v[174:177], v[216:219], v[120:123]
	v_mfma_f32_16x16x32_bf16 v[112:115], v[182:185], v[216:219], v[112:115]
	v_mfma_f32_16x16x32_bf16 v[104:107], v[174:177], v[224:227], v[104:107]
	v_mfma_f32_16x16x32_bf16 v[96:99], v[182:185], v[224:227], v[96:99]
	v_mfma_f32_16x16x32_bf16 v[88:91], v[174:177], v[232:235], v[88:91]
	v_mfma_f32_16x16x32_bf16 v[80:83], v[182:185], v[232:235], v[80:83]
	v_mfma_f32_16x16x32_bf16 v[72:75], v[174:177], v[240:243], v[72:75]
	v_mfma_f32_16x16x32_bf16 v[64:67], v[182:185], v[240:243], v[64:67]
	s_setprio 0
	s_barrier
; #define PG8_STAGE(bufoff, gbase, voff) do { _Pragma("unroll") for (int _i = 0; _i < 2; ++_i) \
;         __builtin_amdgcn_global_load_lds((const unsigned*)((const char*)(gbase) + (voff)[_i]), (PG8_LAS unsigned*)(lds + (bufoff) + ldsw + _i * 8192), 16, 0, 0); } while (0)
; #define PG8_LDA(dst, b, h) do { _Pragma("unroll") for (int m = 0; m < 4; ++m) _Pragma("unroll") for (int k = 0; k < 2; ++k) dst[m][k] = *(const PG8_LAS bf16x8*)(lds + PG8_SA(b, h) + aoff + m * 2048 + k * 1024); } while (0)
; #define PG8_MMA(ai, bj, At, Bt) do { __builtin_amdgcn_s_setprio(1); _Pragma("unroll") for (int m = 0; m < 4; ++m) _Pragma("unroll") for (int n = 0; n < 2; ++n) _Pragma("unroll") for (int k = 0; k < 2; ++k) \
;         acc[ai][bj][m][n] = __builtin_amdgcn_mfma_f32_16x16x32_bf16(Bt[n][k], At[m][k], acc[ai][bj][m][n], 0, 0, 0); __builtin_amdgcn_s_setprio(0); } while (0)
; #define PG8_WAIT_V(n) asm volatile("s_waitcnt vmcnt(" #n ")" ::: "memory")
; #define PG8_WAIT_L(n) asm volatile("s_waitcnt lgkmcnt(" #n ")" ::: "memory")
; #define PG8_BAR __builtin_amdgcn_s_barrier()
; #define PG8_SCHED __builtin_amdgcn_sched_barrier(0)
; template <class Epi, class Sched, bool ALIGN_EPI = false, bool SP2 = false, bool AIMG = false>
; __device__ __forceinline__ void gemm_phase(PG8_LAS unsigned char* lds, const Gemm g, const Sched& S, const Epi& E) {
;     ...
;         for (int t = 0; t < nt; t += 2) {
;     ...
;             PG8_LDA(At, 1, 1); PG8_STAGE(PG8_SB(1, 0), b3, voffB); PG8_STAGE(PG8_SB(1, 1), b3 + hstep, voffB); PG8_STAGE(PG8_SA(1, 0), a3, voffA);
;             PG8_WAIT_V(8); PG8_WAIT_L(0); PG8_BAR; PG8_MMA(1, 0, At, B0); PG8_MMA(1, 1, At, B1); PG8_BAR; PG8_SCHED;
;     ...
;         if constexpr (ALIGN_EPI) { if (wr == 0) PG8_BAR; }
	s_add_i32 s40, s57, s4
	v_lshl_add_u64 v[198:199], v[198:199], 0, s[80:81]
	s_mov_b32 m0, s40
	ds_read_b128 v[190:193], v188 offset:49152
	ds_read_b128 v[216:219], v188 offset:50176
	ds_read_b128 v[220:223], v188 offset:51200
	ds_read_b128 v[224:227], v188 offset:52224
	ds_read_b128 v[228:231], v188 offset:53248
	ds_read_b128 v[232:235], v188 offset:54272
	ds_read_b128 v[236:239], v188 offset:55296
	ds_read_b128 v[240:243], v188 offset:56320
	global_load_lds_dwordx4 v[198:199], off
	s_add_i32 m0, s40, 0x2000
	s_add_u32 s36, s36, 0x40080
	v_lshl_add_u64 v[198:199], v[200:201], 0, s[80:81]
	s_addc_u32 s37, s37, 0
	s_add_i32 s40, s58, s4
	global_load_lds_dwordx4 v[198:199], off
	v_lshl_add_u64 v[198:199], s[36:37], 0, v[156:157]
	s_mov_b32 m0, s40
	s_nop 0
	global_load_lds_dwordx4 v[198:199], off
	v_lshl_add_u64 v[198:199], s[36:37], 0, v[152:153]
	s_add_i32 m0, s40, 0x2000
	s_nop 0
	global_load_lds_dwordx4 v[198:199], off
	v_lshl_add_u64 v[198:199], v[204:205], 0, s[80:81]
	s_mov_b32 m0, s46
	s_nop 0
	global_load_lds_dwordx4 v[198:199], off
	v_lshl_add_u64 v[198:199], v[206:207], 0, s[80:81]
	s_mov_b32 m0, s47
	s_nop 0
	global_load_lds_dwordx4 v[198:199], off
	s_waitcnt vmcnt(8)
	s_waitcnt lgkmcnt(0)
	s_barrier
	s_setprio 1
	s_waitcnt lgkmcnt(0)
	v_mfma_f32_16x16x32_bf16 v[60:63], v[128:131], v[190:193], v[60:63]
	v_mfma_f32_16x16x32_bf16 v[52:55], v[136:139], v[190:193], v[52:55]
	v_mfma_f32_16x16x32_bf16 v[44:47], v[128:131], v[220:223], v[44:47]
	v_mfma_f32_16x16x32_bf16 v[36:39], v[136:139], v[220:223], v[36:39]
	v_mfma_f32_16x16x32_bf16 v[28:31], v[128:131], v[228:231], v[28:31]
	v_mfma_f32_16x16x32_bf16 v[20:23], v[136:139], v[228:231], v[20:23]
	v_mfma_f32_16x16x32_bf16 v[12:15], v[128:131], v[236:239], v[12:15]
	v_mfma_f32_16x16x32_bf16 v[4:7], v[136:139], v[236:239], v[4:7]
	v_mfma_f32_16x16x32_bf16 v[60:63], v[132:135], v[216:219], v[60:63]
	v_mfma_f32_16x16x32_bf16 v[52:55], v[140:143], v[216:219], v[52:55]
	v_mfma_f32_16x16x32_bf16 v[44:47], v[132:135], v[224:227], v[44:47]
	v_mfma_f32_16x16x32_bf16 v[36:39], v[140:143], v[224:227], v[36:39]
	v_mfma_f32_16x16x32_bf16 v[28:31], v[132:135], v[232:235], v[28:31]
	v_mfma_f32_16x16x32_bf16 v[20:23], v[140:143], v[232:235], v[20:23]
	v_mfma_f32_16x16x32_bf16 v[12:15], v[132:135], v[240:243], v[12:15]
	v_mfma_f32_16x16x32_bf16 v[4:7], v[140:143], v[240:243], v[4:7]
	s_setprio 0
	s_setprio 1
	v_mfma_f32_16x16x32_bf16 v[56:59], v[170:173], v[190:193], v[56:59]
	v_mfma_f32_16x16x32_bf16 v[48:51], v[178:181], v[190:193], v[48:51]
	v_mfma_f32_16x16x32_bf16 v[40:43], v[170:173], v[220:223], v[40:43]
	v_mfma_f32_16x16x32_bf16 v[32:35], v[178:181], v[220:223], v[32:35]
	v_mfma_f32_16x16x32_bf16 v[24:27], v[170:173], v[228:231], v[24:27]
	v_mfma_f32_16x16x32_bf16 v[16:19], v[178:181], v[228:231], v[16:19]
	v_mfma_f32_16x16x32_bf16 v[8:11], v[170:173], v[236:239], v[8:11]
	v_mfma_f32_16x16x32_bf16 v[0:3], v[178:181], v[236:239], v[0:3]
	v_mfma_f32_16x16x32_bf16 v[56:59], v[174:177], v[216:219], v[56:59]
	v_mfma_f32_16x16x32_bf16 v[48:51], v[182:185], v[216:219], v[48:51]
	v_mfma_f32_16x16x32_bf16 v[40:43], v[174:177], v[224:227], v[40:43]
	v_mfma_f32_16x16x32_bf16 v[32:35], v[182:185], v[224:227], v[32:35]
	v_mfma_f32_16x16x32_bf16 v[24:27], v[174:177], v[232:235], v[24:27]
	v_mfma_f32_16x16x32_bf16 v[16:19], v[182:185], v[232:235], v[16:19]
	v_mfma_f32_16x16x32_bf16 v[8:11], v[174:177], v[240:243], v[8:11]
	v_mfma_f32_16x16x32_bf16 v[0:3], v[182:185], v[240:243], v[0:3]
	s_setprio 0
	s_barrier
	s_add_i32 s56, s56, 2
	s_add_u32 s28, s28, 0x100
	s_addc_u32 s29, s29, 0
	s_add_u32 s54, s54, 0x100
	s_addc_u32 s55, s55, 0
	s_cmp_gt_u32 s56, 13
	s_cbranch_scc0 .LBB0_286
	s_and_b64 vcc, exec, s[16:17]
	s_cbranch_vccz .LBB0_289
	s_barrier

; __device__ __forceinline__ void phase_merge(const KP2& p, int l, LAS unsigned char* lds) {
;     ...
;     for (int s = 0; s < NS; ++s) {
;         if (s + 1 < NS) asm volatile("s_waitcnt vmcnt(6)" ::: "memory"); else asm volatile("s_waitcnt vmcnt(0)" ::: "memory");
;         __builtin_amdgcn_s_barrier(); asm volatile("" ::: "memory");
.LBB0_596:
	s_andn2_b64 vcc, exec, s[6:7]
	s_cbranch_vccnz .LBB0_598
	s_and_b32 s100, s22, 3
	s_cmp_eq_u32 s100, 1
	s_cbranch_scc1 .Lmrg_w10
	s_waitcnt vmcnt(6)
	s_branch .LBB0_598
.Lmrg_w10:
	s_waitcnt vmcnt(10)
